# S5 pass 2 block loop: counted waits (next-block and skip-input loads stay in flight under the scan)
# speedup vs baseline: 1.0171x; 1.0012x over previous
; template <bool FIX>
; __device__ __forceinline__ void ssm_block32(const bf16x8& au, const SsmUnit& U, float (&Hr)[2], float (&Hi)[2], float (&H1r)[2], float (&H1i)[2], f32x16 (&Dr)[2], f32x16 (&Di)[2], int h) {
;     f32x16 z;
; #pragma unroll
;     for (int i = 0; i < 16; ++i) z[i] = 0.f;
; #pragma unroll
;     for (int s = 0; s < 2; ++s) { Dr[s] = MFMA32(au, U.bfr[2 * s], z); Di[s] = MFMA32(au, U.bfr[2 * s + 1], z); }
; #pragma unroll
;     for (int s = 0; s < 2; ++s) {
;         const float ar = U.pw[s].r[0], ai = U.pw[s].i[0], a4r = U.pw[s].r[3], a4i = U.pw[s].i[3];
; #pragma unroll
;         for (int j = 0; j < 4; ++j)
; #pragma unroll
;             for (int e = 1; e < 4; ++e) { const int i = 4 * j + e;
;                 const float nr = ar * Dr[s][i - 1] - ai * Di[s][i - 1] + Dr[s][i], ni = ar * Di[s][i - 1] + ai * Dr[s][i - 1] + Di[s][i]; Dr[s][i] = nr; Di[s][i] = ni; }
;         float hr = Hr[s], hi = Hi[s];
; #pragma unroll
;         for (int j = 0; j < 4; ++j) {
;             const float ownr = Dr[s][4 * j + 3], owni = Di[s][4 * j + 3], othr = __shfl_xor(ownr, 32), othi = __shfl_xor(owni, 32);
;             const float evr = h ? othr : ownr, evi = h ? othi : owni, odr = h ? ownr : othr, odi = h ? owni : othi;
;             const float inr0 = hr, ini0 = hi;
;             float t = a4r * hr - a4i * hi + evr; hi = a4r * hi + a4i * hr + evi; hr = t;
;             if (j == 0) { H1r[s] = hr; H1i[s] = hi; }
;             const float inr1 = hr, ini1 = hi;
;             t = a4r * hr - a4i * hi + odr; hi = a4r * hi + a4i * hr + odi; hr = t;
;             if (FIX) { const float inr = h ? inr1 : inr0, ini = h ? ini1 : ini0;
; #pragma unroll
;                 for (int e = 0; e < 4; ++e) { const int i = 4 * j + e; Dr[s][i] += U.pw[s].r[e] * inr - U.pw[s].i[e] * ini; Di[s][i] += U.pw[s].r[e] * ini + U.pw[s].i[e] * inr; } }
;         }
;         Hr[s] = hr; Hi[s] = hi;
;     }
; __device__ __forceinline__ void s3_ssm_pass2(Frame& F, int l) {
;     ...
; #pragma unroll 1
;         for (int blk = 0; blk < nblk; ++blk) {
;             const bf16x8 an = ssm_load_au(P, m0 + 32 * ((blk + 1) & 3), ntok, g, lane);
;             u32x2 uw[2];
; #pragma unroll
;             for (int tt = 0; tt < 2; ++tt) uw[tt] = (16 * tt + tk < ntok) ? *(const u32x2*)(P + (size_t)(m0 + 32 * blk + 16 * tt + tk) * NPROJ + C_SU + g * 16 + 4 * cq) : (u32x2){0u, 0u};
;             f32x16 Dr[2], Di[2];
.LBB0_719:
	s_or_b64 exec, exec, s[22:23]
	s_cmp_eq_u64 s[48:49], 0
	s_cbranch_scc1 .Lp2_w2
	s_waitcnt vmcnt(3)
	s_branch .Lp2_wd
.Lp2_w2:
	s_waitcnt vmcnt(2)
.Lp2_wd:
	v_mfma_f32_32x32x16_bf16 v[2:17], v[50:53], v[74:77], 0
	v_mfma_f32_32x32x16_bf16 v[18:33], v[50:53], v[70:73], 0
	s_nop 10
	v_mul_f32_e64 v34, v156, v2
	v_mul_f32_e64 v35, v157, v2
	v_mul_f32_e64 v172, v156, v10
	v_mul_f32_e64 v173, v157, v10
	v_pk_fma_f32 v[36:37], v[66:67], v[18:19], v[34:35] neg_lo:[0,0,1] neg_hi:[0,0,1]
	v_pk_fma_f32 v[34:35], v[66:67], v[18:19], v[34:35] op_sel_hi:[1,0,1]
	v_pk_fma_f32 v[174:175], v[66:67], v[26:27], v[172:173] neg_lo:[0,0,1] neg_hi:[0,0,1]
	v_mov_b32_e32 v37, v35
	v_mov_b32_e32 v34, v19
	v_mov_b32_e32 v35, v3
	v_pk_add_f32 v[186:187], v[34:35], v[36:37]
	v_pk_fma_f32 v[172:173], v[66:67], v[26:27], v[172:173] op_sel_hi:[1,0,1]
	v_pk_mul_f32 v[34:35], v[66:67], v[186:187]
	v_mov_b32_e32 v175, v173
	v_sub_f32_e32 v3, v34, v35
	v_pk_mul_f32 v[34:35], v[156:157], v[186:187]
	v_add_f32_e32 v188, v20, v3
	v_add_f32_e32 v3, v34, v35
	v_pk_mul_f32 v[34:35], v[156:157], v[6:7] op_sel_hi:[1,0]
	v_add_f32_e32 v184, v4, v3
	v_pk_fma_f32 v[36:37], v[66:67], v[22:23], v[34:35] neg_lo:[0,0,1] neg_hi:[0,0,1]
	v_pk_fma_f32 v[34:35], v[66:67], v[22:23], v[34:35] op_sel_hi:[1,0,1]
	v_mov_b32_e32 v172, v27
	v_mov_b32_e32 v37, v35
	v_mov_b32_e32 v34, v23
	v_mov_b32_e32 v35, v7
	v_pk_add_f32 v[178:179], v[34:35], v[36:37]
	v_mov_b32_e32 v173, v11
	v_pk_mul_f32 v[54:55], v[66:67], v[178:179]
	v_mfma_f32_32x32x16_bf16 v[34:49], v[50:53], v[82:85], 0
	v_sub_f32_e32 v3, v54, v55
	v_mul_f32_e64 v54, v156, v178
	v_mul_f32_e64 v55, v157, v179
	v_add_f32_e32 v182, v24, v3
	v_add_f32_e32 v3, v54, v55
	v_pk_add_f32 v[174:175], v[172:173], v[174:175]
	v_add_f32_e32 v180, v8, v3
	v_pk_mul_f32 v[172:173], v[66:67], v[174:175]
	v_mfma_f32_32x32x16_bf16 v[50:65], v[50:53], v[86:89], 0
	v_sub_f32_e32 v3, v172, v173
	v_mul_f32_e64 v172, v156, v174
	v_mul_f32_e64 v173, v157, v175
	v_add_f32_e32 v176, v28, v3
	v_add_f32_e32 v3, v172, v173
	v_pk_mul_f32 v[172:173], v[156:157], v[14:15] op_sel_hi:[1,0]
	v_add_f32_e32 v28, v12, v3
	v_pk_fma_f32 v[190:191], v[66:67], v[30:31], v[172:173] neg_lo:[0,0,1] neg_hi:[0,0,1]
	v_pk_fma_f32 v[172:173], v[66:67], v[30:31], v[172:173] op_sel_hi:[1,0,1]
	v_mov_b32_e32 v198, v34
	v_mov_b32_e32 v191, v173
	v_mov_b32_e32 v172, v31
	v_mov_b32_e32 v173, v15
	v_pk_add_f32 v[172:173], v[172:173], v[190:191]
	v_mov_b32_e32 v199, v50
	v_pk_mul_f32 v[190:191], v[66:67], v[172:173]
	v_mul_f32_e32 v4, v79, v50
	v_sub_f32_e32 v3, v190, v191
	v_pk_mul_f32 v[190:191], v[156:157], v[172:173]
	v_add_f32_e32 v24, v32, v3
	v_add_f32_e32 v3, v190, v191
	v_pk_fma_f32 v[200:201], v[78:79], v[198:199], v[4:5] op_sel_hi:[1,1,0] neg_lo:[0,0,1] neg_hi:[0,0,1]
	v_mov_b32_e32 v190, v50
	v_mov_b32_e32 v191, v34
	v_mul_f32_e32 v4, v78, v50
	v_pk_fma_f32 v[210:211], v[78:79], v[190:191], v[4:5] op_sel_hi:[1,1,0]
	v_mov_b32_e32 v50, v35
	v_mov_b32_e32 v201, v211
	v_pk_add_f32 v[200:201], v[50:51], v[200:201]
	v_mov_b32_e32 v212, v36
	v_pk_mul_f32 v[34:35], v[160:161], v[200:201] op_sel:[0,1]
	v_mov_b32_e32 v213, v52
	v_pk_fma_f32 v[50:51], v[78:79], v[200:201], v[34:35] neg_lo:[0,0,1] neg_hi:[0,0,1]
	v_pk_fma_f32 v[34:35], v[78:79], v[200:201], v[34:35] op_sel_hi:[1,0,1]
	v_mov_b32_e32 v214, v38
	v_mov_b32_e32 v51, v35
	v_pk_add_f32 v[210:211], v[212:213], v[50:51]
	v_mov_b32_e32 v215, v54
	v_mul_f32_e32 v8, v79, v211
	v_mul_f32_e32 v4, v79, v54
	v_pk_fma_f32 v[34:35], v[78:79], v[210:211], v[8:9] op_sel_hi:[1,1,0] neg_lo:[0,0,1] neg_hi:[0,0,1]
	v_mul_f32_e32 v8, v160, v210
	v_pk_fma_f32 v[216:217], v[78:79], v[214:215], v[4:5] op_sel_hi:[1,1,0] neg_lo:[0,0,1] neg_hi:[0,0,1]
	v_mov_b32_e32 v190, v54
	v_mov_b32_e32 v191, v38
	v_mul_f32_e32 v4, v78, v54
	v_pk_fma_f32 v[50:51], v[160:161], v[210:211], v[8:9] op_sel_hi:[1,1,0]
	v_pk_fma_f32 v[218:219], v[78:79], v[190:191], v[4:5] op_sel_hi:[1,1,0]
	v_mov_b32_e32 v222, v42
	v_mov_b32_e32 v223, v58
	v_mul_f32_e32 v4, v79, v58
	v_mov_b32_e32 v52, v37
	v_mov_b32_e32 v35, v51
	v_pk_fma_f32 v[224:225], v[78:79], v[222:223], v[4:5] op_sel_hi:[1,1,0] neg_lo:[0,0,1] neg_hi:[0,0,1]
	v_mov_b32_e32 v190, v58
	v_mov_b32_e32 v191, v42
	v_mul_f32_e32 v4, v78, v58
	v_pk_add_f32 v[36:37], v[52:53], v[34:35]
	v_add_f32_e32 v20, v16, v3
	v_pk_fma_f32 v[226:227], v[78:79], v[190:191], v[4:5] op_sel_hi:[1,1,0]
	v_mov_b32_e32 v190, v46
	v_mov_b32_e32 v191, v62
	v_mul_f32_e32 v4, v79, v62
	ds_bpermute_b32 v3, v119, v37
	ds_bpermute_b32 v7, v119, v36
	v_pk_fma_f32 v[192:193], v[78:79], v[190:191], v[4:5] op_sel_hi:[1,1,0] neg_lo:[0,0,1] neg_hi:[0,0,1]
	v_mov_b32_e32 v194, v62
	v_mov_b32_e32 v195, v46
	v_mul_f32_e32 v4, v78, v62
	v_pk_fma_f32 v[206:207], v[78:79], v[194:195], v[4:5] op_sel_hi:[1,1,0]
	v_mul_f32_e32 v4, v151, v167
	v_pk_fma_f32 v[34:35], v[150:151], v[166:167], v[4:5] op_sel_hi:[1,1,0] neg_lo:[0,0,1] neg_hi:[0,0,1]
	v_mul_f32_e32 v4, v158, v166
	v_pk_fma_f32 v[50:51], v[158:159], v[166:167], v[4:5] op_sel_hi:[1,1,0]
	s_waitcnt lgkmcnt(1)
	v_cndmask_b32_e64 v53, v3, v37, s[40:41]
	s_waitcnt lgkmcnt(0)
; template <bool FIX>
; __device__ __forceinline__ void ssm_block32(const bf16x8& au, const SsmUnit& U, float (&Hr)[2], float (&Hi)[2], float (&H1r)[2], float (&H1i)[2], f32x16 (&Dr)[2], f32x16 (&Di)[2], int h) {
;     ...
;     for (int s = 0; s < 2; ++s) {
;         const float ar = U.pw[s].r[0], ai = U.pw[s].i[0], a4r = U.pw[s].r[3], a4i = U.pw[s].i[3];
; #pragma unroll
;         for (int j = 0; j < 4; ++j)
; #pragma unroll
;             for (int e = 1; e < 4; ++e) { const int i = 4 * j + e;
;                 const float nr = ar * Dr[s][i - 1] - ai * Di[s][i - 1] + Dr[s][i], ni = ar * Di[s][i - 1] + ai * Dr[s][i - 1] + Di[s][i]; Dr[s][i] = nr; Di[s][i] = ni; }
;         float hr = Hr[s], hi = Hi[s];
; #pragma unroll
;         for (int j = 0; j < 4; ++j) {
;             const float ownr = Dr[s][4 * j + 3], owni = Di[s][4 * j + 3], othr = __shfl_xor(ownr, 32), othi = __shfl_xor(owni, 32);
;             const float evr = h ? othr : ownr, evi = h ? othi : owni, odr = h ? ownr : othr, odi = h ? owni : othi;
;             const float inr0 = hr, ini0 = hi;
;             float t = a4r * hr - a4i * hi + evr; hi = a4r * hi + a4i * hr + evi; hr = t;
;             if (j == 0) { H1r[s] = hr; H1i[s] = hi; }
;             const float inr1 = hr, ini1 = hi;
;             t = a4r * hr - a4i * hi + odr; hi = a4r * hi + a4i * hr + odi; hr = t;
;             if (FIX) { const float inr = h ? inr1 : inr0, ini = h ? ini1 : ini0;
; #pragma unroll
;                 for (int e = 0; e < 4; ++e) { const int i = 4 * j + e; Dr[s][i] += U.pw[s].r[e] * inr - U.pw[s].i[e] * ini; Di[s][i] += U.pw[s].r[e] * ini + U.pw[s].i[e] * inr; } }
;         }
;         Hr[s] = hr; Hi[s] = hi;
	v_cndmask_b32_e64 v52, v7, v36, s[40:41]
	v_mov_b32_e32 v35, v51
	v_pk_add_f32 v[34:35], v[34:35], v[52:53]
	v_mov_b32_e32 v54, v39
	v_mul_f32_e32 v4, v151, v35
	v_pk_fma_f32 v[212:213], v[150:151], v[34:35], v[4:5] op_sel_hi:[1,1,0] neg_lo:[0,0,1] neg_hi:[0,0,1]
	v_mul_f32_e32 v4, v158, v34
	v_cndmask_b32_e64 v167, v35, v167, s[40:41]
	v_pk_fma_f32 v[230:231], v[158:159], v[34:35], v[4:5] op_sel_hi:[1,1,0]
	v_mov_b32_e32 v4, v167
	v_cndmask_b32_e64 v166, v34, v166, s[40:41]
	v_pk_mul_f32 v[50:51], v[160:161], v[4:5] op_sel_hi:[1,0]
	v_mov_b32_e32 v217, v219
	v_pk_fma_f32 v[52:53], v[78:79], v[166:167], v[50:51] neg_lo:[0,0,1] neg_hi:[0,0,1]
	v_pk_fma_f32 v[50:51], v[78:79], v[166:167], v[50:51] op_sel_hi:[1,0,1]
	v_pk_add_f32 v[38:39], v[54:55], v[216:217]
	v_mov_b32_e32 v53, v51
	v_pk_add_f32 v[50:51], v[198:199], v[52:53]
	v_pk_mul_f32 v[52:53], v[140:141], v[166:167]
	v_pk_mul_f32 v[54:55], v[78:79], v[38:39] op_sel:[0,1]
	v_pk_fma_f32 v[198:199], v[144:145], v[166:167], v[52:53] op_sel:[0,0,1] op_sel_hi:[1,1,0] neg_lo:[0,0,1] neg_hi:[0,0,1]
	v_pk_fma_f32 v[52:53], v[144:145], v[166:167], v[52:53] op_sel:[0,0,1] op_sel_hi:[1,1,0]
	v_mov_b32_e32 v220, v56
	v_mov_b32_e32 v199, v53
	v_pk_add_f32 v[52:53], v[200:201], v[198:199]
	v_pk_mul_f32 v[198:199], v[138:139], v[166:167]
	v_mov_b32_e32 v221, v40
	v_pk_fma_f32 v[200:201], v[142:143], v[166:167], v[198:199] op_sel:[0,0,1] op_sel_hi:[1,1,0] neg_lo:[0,0,1] neg_hi:[0,0,1]
	v_pk_fma_f32 v[198:199], v[142:143], v[166:167], v[198:199] op_sel:[0,0,1] op_sel_hi:[1,1,0]
	v_mov_b32_e32 v56, v41
	v_mov_b32_e32 v201, v199
	v_pk_add_f32 v[198:199], v[210:211], v[200:201]
	v_pk_mul_f32 v[200:201], v[158:159], v[4:5] op_sel_hi:[1,0]
	v_mov_b32_e32 v213, v231
	v_pk_fma_f32 v[210:211], v[150:151], v[166:167], v[200:201] neg_lo:[0,0,1] neg_hi:[0,0,1]
	v_pk_fma_f32 v[166:167], v[150:151], v[166:167], v[200:201] op_sel_hi:[1,0,1]
	v_pk_fma_f32 v[200:201], v[160:161], v[38:39], v[54:55] op_sel_hi:[1,0,1] neg_lo:[0,0,1] neg_hi:[0,0,1]
	v_pk_fma_f32 v[54:55], v[160:161], v[38:39], v[54:55] op_sel_hi:[1,0,1]
	v_mov_b32_e32 v211, v167
	v_mov_b32_e32 v55, v201
	v_pk_add_f32 v[54:55], v[220:221], v[54:55]
	v_pk_add_f32 v[166:167], v[36:37], v[210:211]
	v_mul_f32_e32 v4, v79, v54
	v_pk_fma_f32 v[200:201], v[78:79], v[54:55], v[4:5] op_sel:[0,1,0] op_sel_hi:[1,0,0] neg_lo:[0,0,1] neg_hi:[0,0,1]
	v_mul_f32_e32 v4, v78, v54
	v_pk_fma_f32 v[210:211], v[78:79], v[54:55], v[4:5] op_sel_hi:[1,1,0]
	v_cndmask_b32_e64 v37, v37, v3, s[40:41]
	v_mov_b32_e32 v201, v211
	v_pk_add_f32 v[40:41], v[56:57], v[200:201]
	ds_bpermute_b32 v3, v119, v41
	ds_bpermute_b32 v8, v119, v40
	v_cndmask_b32_e64 v36, v36, v7, s[40:41]
	v_pk_add_f32 v[36:37], v[36:37], v[212:213]
	v_mov_b32_e32 v58, v43
	v_pk_mul_f32 v[200:201], v[158:159], v[36:37] op_sel:[0,1]
	s_waitcnt lgkmcnt(1)
	v_cndmask_b32_e64 v57, v3, v41, s[40:41]
	v_pk_fma_f32 v[210:211], v[150:151], v[36:37], v[200:201] neg_lo:[0,0,1] neg_hi:[0,0,1]
	v_pk_fma_f32 v[200:201], v[150:151], v[36:37], v[200:201] op_sel_hi:[1,0,1]
	s_waitcnt lgkmcnt(0)
	v_cndmask_b32_e64 v56, v8, v40, s[40:41]
	v_mov_b32_e32 v211, v201
	v_pk_add_f32 v[56:57], v[56:57], v[210:211]
	v_mov_b32_e32 v225, v227
	v_mul_f32_e32 v4, v151, v57
	v_pk_fma_f32 v[200:201], v[150:151], v[56:57], v[4:5] op_sel_hi:[1,1,0] neg_lo:[0,0,1] neg_hi:[0,0,1]
	v_mul_f32_e32 v4, v158, v56
	v_cndmask_b32_e64 v37, v57, v37, s[40:41]
	v_pk_fma_f32 v[210:211], v[158:159], v[56:57], v[4:5] op_sel_hi:[1,1,0]
	v_mov_b32_e32 v4, v37
	v_cndmask_b32_e64 v36, v56, v36, s[40:41]
	v_pk_mul_f32 v[56:57], v[160:161], v[4:5] op_sel_hi:[1,0]
	v_mov_b32_e32 v228, v60
	v_pk_fma_f32 v[212:213], v[78:79], v[36:37], v[56:57] neg_lo:[0,0,1] neg_hi:[0,0,1]
	v_pk_fma_f32 v[56:57], v[78:79], v[36:37], v[56:57] op_sel_hi:[1,0,1]
	v_mov_b32_e32 v229, v44
	v_mov_b32_e32 v213, v57
	v_pk_add_f32 v[56:57], v[214:215], v[212:213]
	v_pk_mul_f32 v[212:213], v[140:141], v[36:37]
	v_mov_b32_e32 v60, v45
	v_pk_fma_f32 v[214:215], v[144:145], v[36:37], v[212:213] op_sel:[0,0,1] op_sel_hi:[1,1,0] neg_lo:[0,0,1] neg_hi:[0,0,1]
	v_pk_fma_f32 v[212:213], v[144:145], v[36:37], v[212:213] op_sel:[0,0,1] op_sel_hi:[1,1,0]
	v_mov_b32_e32 v201, v211
	v_mov_b32_e32 v215, v213
	v_pk_add_f32 v[212:213], v[38:39], v[214:215]
	v_pk_mul_f32 v[38:39], v[138:139], v[36:37]
	v_mov_b32_e32 v62, v47
	v_pk_fma_f32 v[214:215], v[142:143], v[36:37], v[38:39] op_sel:[0,0,1] op_sel_hi:[1,1,0] neg_lo:[0,0,1] neg_hi:[0,0,1]
	v_pk_fma_f32 v[38:39], v[142:143], v[36:37], v[38:39] op_sel:[0,0,1] op_sel_hi:[1,1,0]
	v_mov_b32_e32 v193, v207
	v_mov_b32_e32 v215, v39
	v_pk_mul_f32 v[38:39], v[148:149], v[36:37]
	v_pk_add_f32 v[54:55], v[54:55], v[214:215] op_sel:[1,0] op_sel_hi:[0,1]
	v_pk_fma_f32 v[214:215], v[146:147], v[36:37], v[38:39] op_sel:[0,0,1] op_sel_hi:[1,1,0] neg_lo:[0,0,1] neg_hi:[0,0,1]
	v_pk_fma_f32 v[36:37], v[146:147], v[36:37], v[38:39] op_sel:[0,0,1] op_sel_hi:[1,1,0]
	v_pk_add_f32 v[46:47], v[62:63], v[192:193]
	v_mov_b32_e32 v215, v37
	v_pk_add_f32 v[36:37], v[58:59], v[224:225]
	v_pk_add_f32 v[214:215], v[40:41], v[214:215]
	v_pk_mul_f32 v[38:39], v[78:79], v[36:37] op_sel:[0,1]
	v_cndmask_b32_e64 v41, v41, v3, s[40:41]
	v_pk_fma_f32 v[42:43], v[160:161], v[36:37], v[38:39] op_sel_hi:[1,0,1] neg_lo:[0,0,1] neg_hi:[0,0,1]
	v_pk_fma_f32 v[38:39], v[160:161], v[36:37], v[38:39] op_sel_hi:[1,0,1]
	v_cndmask_b32_e64 v40, v40, v8, s[40:41]
	v_mov_b32_e32 v39, v43
	v_pk_add_f32 v[38:39], v[228:229], v[38:39]
	v_pk_add_f32 v[40:41], v[40:41], v[200:201]
	v_mul_f32_e32 v4, v79, v38
	v_pk_fma_f32 v[42:43], v[78:79], v[38:39], v[4:5] op_sel:[0,1,0] op_sel_hi:[1,0,0] neg_lo:[0,0,1] neg_hi:[0,0,1]
	v_mul_f32_e32 v4, v78, v38
	v_pk_fma_f32 v[58:59], v[78:79], v[38:39], v[4:5] op_sel_hi:[1,1,0]
	v_mov_b32_e32 v194, v64
	v_mov_b32_e32 v43, v59
	v_pk_add_f32 v[42:43], v[60:61], v[42:43]
	ds_bpermute_b32 v3, v119, v43
	ds_bpermute_b32 v7, v119, v42
	v_pk_mul_f32 v[58:59], v[158:159], v[40:41] op_sel:[0,1]
	v_mov_b32_e32 v195, v48
	v_pk_fma_f32 v[60:61], v[150:151], v[40:41], v[58:59] neg_lo:[0,0,1] neg_hi:[0,0,1]
	v_pk_fma_f32 v[58:59], v[150:151], v[40:41], v[58:59] op_sel_hi:[1,0,1]
	s_waitcnt lgkmcnt(1)
; #define LAS __attribute__((address_space(3)))
; __device__ __forceinline__ unsigned pk2(float lo, float hi) { f32x2 v = {lo, hi}; bf16x2_t b = __builtin_convertvector(v, bf16x2_t); return __builtin_bit_cast(unsigned, b); }
; template <bool FIX>
; __device__ __forceinline__ void ssm_block32(const bf16x8& au, const SsmUnit& U, float (&Hr)[2], float (&Hi)[2], float (&H1r)[2], float (&H1i)[2], f32x16 (&Dr)[2], f32x16 (&Di)[2], int h) {
;     ...
;     for (int s = 0; s < 2; ++s) {
;         const float ar = U.pw[s].r[0], ai = U.pw[s].i[0], a4r = U.pw[s].r[3], a4i = U.pw[s].i[3];
; #pragma unroll
;         for (int j = 0; j < 4; ++j)
; #pragma unroll
;             for (int e = 1; e < 4; ++e) { const int i = 4 * j + e;
;                 const float nr = ar * Dr[s][i - 1] - ai * Di[s][i - 1] + Dr[s][i], ni = ar * Di[s][i - 1] + ai * Dr[s][i - 1] + Di[s][i]; Dr[s][i] = nr; Di[s][i] = ni; }
;         float hr = Hr[s], hi = Hi[s];
; #pragma unroll
;         for (int j = 0; j < 4; ++j) {
;             const float ownr = Dr[s][4 * j + 3], owni = Di[s][4 * j + 3], othr = __shfl_xor(ownr, 32), othi = __shfl_xor(owni, 32);
;             const float evr = h ? othr : ownr, evi = h ? othi : owni, odr = h ? ownr : othr, odi = h ? owni : othi;
;             const float inr0 = hr, ini0 = hi;
;             float t = a4r * hr - a4i * hi + evr; hi = a4r * hi + a4i * hr + evi; hr = t;
;             if (j == 0) { H1r[s] = hr; H1i[s] = hi; }
;             const float inr1 = hr, ini1 = hi;
;             t = a4r * hr - a4i * hi + odr; hi = a4r * hi + a4i * hr + odi; hr = t;
;             if (FIX) { const float inr = h ? inr1 : inr0, ini = h ? ini1 : ini0;
; #pragma unroll
;                 for (int e = 0; e < 4; ++e) { const int i = 4 * j + e; Dr[s][i] += U.pw[s].r[e] * inr - U.pw[s].i[e] * ini; Di[s][i] += U.pw[s].r[e] * ini + U.pw[s].i[e] * inr; } }
;         }
;         Hr[s] = hr; Hi[s] = hi;
; __device__ __forceinline__ void s3_ssm_pass2(Frame& F, int l) {
;     ...
; #pragma unroll
;             for (int i = 0; i < 16; ++i) { const int tl = (i & 3) + 8 * (i >> 2) + 4 * h;
;                 *(LAS unsigned*)(himg + tl * 272 + 4 * n32) = pk2(Dr[0][i], Di[0][i]); *(LAS unsigned*)(himg + tl * 272 + 4 * (32 + n32)) = pk2(Dr[1][i], Di[1][i]); }
	v_cndmask_b32_e64 v45, v3, v43, s[40:41]
	s_waitcnt lgkmcnt(0)
	v_cndmask_b32_e64 v44, v7, v42, s[40:41]
	v_mov_b32_e32 v61, v59
	v_pk_add_f32 v[44:45], v[44:45], v[60:61]
	v_mov_b32_e32 v64, v49
	v_cndmask_b32_e64 v41, v45, v41, s[40:41]
	v_mov_b32_e32 v4, v41
	v_cndmask_b32_e64 v40, v44, v40, s[40:41]
	v_pk_mul_f32 v[58:59], v[160:161], v[4:5] op_sel_hi:[1,0]
	v_mul_f32_e32 v4, v158, v44
	v_pk_fma_f32 v[60:61], v[78:79], v[40:41], v[58:59] neg_lo:[0,0,1] neg_hi:[0,0,1]
	v_pk_fma_f32 v[58:59], v[78:79], v[40:41], v[58:59] op_sel_hi:[1,0,1]
	v_mov_b32_e32 v16, v33
	v_mov_b32_e32 v61, v59
	v_pk_add_f32 v[58:59], v[222:223], v[60:61]
	v_pk_mul_f32 v[60:61], v[140:141], v[40:41]
	v_mov_b32_e32 v19, v2
	v_pk_fma_f32 v[200:201], v[144:145], v[40:41], v[60:61] op_sel:[0,0,1] op_sel_hi:[1,1,0] neg_lo:[0,0,1] neg_hi:[0,0,1]
	v_pk_fma_f32 v[60:61], v[144:145], v[40:41], v[60:61] op_sel:[0,0,1] op_sel_hi:[1,1,0]
	v_mov_b32_e32 v27, v10
	v_mov_b32_e32 v201, v61
	v_pk_add_f32 v[60:61], v[36:37], v[200:201]
	v_pk_mul_f32 v[36:37], v[138:139], v[40:41]
	v_mov_b32_e32 v31, v14
	v_pk_fma_f32 v[200:201], v[142:143], v[40:41], v[36:37] op_sel:[0,0,1] op_sel_hi:[1,1,0] neg_lo:[0,0,1] neg_hi:[0,0,1]
	v_pk_fma_f32 v[36:37], v[142:143], v[40:41], v[36:37] op_sel:[0,0,1] op_sel_hi:[1,1,0]
	s_nop 0
	v_mov_b32_e32 v201, v37
	v_pk_mul_f32 v[36:37], v[148:149], v[40:41]
	v_pk_add_f32 v[200:201], v[38:39], v[200:201] op_sel:[1,0] op_sel_hi:[0,1]
	v_pk_fma_f32 v[38:39], v[146:147], v[40:41], v[36:37] op_sel:[0,0,1] op_sel_hi:[1,1,0] neg_lo:[0,0,1] neg_hi:[0,0,1]
	v_pk_fma_f32 v[36:37], v[146:147], v[40:41], v[36:37] op_sel:[0,0,1] op_sel_hi:[1,1,0]
	s_nop 0
	v_mov_b32_e32 v39, v37
	v_pk_mul_f32 v[36:37], v[78:79], v[46:47] op_sel:[0,1]
	v_pk_add_f32 v[40:41], v[42:43], v[38:39]
	v_pk_fma_f32 v[62:63], v[160:161], v[46:47], v[36:37] op_sel_hi:[1,0,1] neg_lo:[0,0,1] neg_hi:[0,0,1]
	v_pk_fma_f32 v[36:37], v[160:161], v[46:47], v[36:37] op_sel_hi:[1,0,1]
	v_pk_fma_f32 v[38:39], v[158:159], v[44:45], v[4:5] op_sel_hi:[1,1,0]
	v_mov_b32_e32 v37, v63
	v_mul_f32_e32 v4, v151, v45
	v_pk_add_f32 v[62:63], v[194:195], v[36:37]
	v_pk_fma_f32 v[44:45], v[150:151], v[44:45], v[4:5] op_sel_hi:[1,1,0] neg_lo:[0,0,1] neg_hi:[0,0,1]
	v_mul_f32_e32 v4, v79, v62
	v_pk_fma_f32 v[36:37], v[78:79], v[62:63], v[4:5] op_sel:[0,1,0] op_sel_hi:[1,0,0] neg_lo:[0,0,1] neg_hi:[0,0,1]
	v_mul_f32_e32 v4, v78, v62
	v_pk_fma_f32 v[192:193], v[78:79], v[62:63], v[4:5] op_sel_hi:[1,1,0]
	v_cndmask_b32_e64 v43, v43, v3, s[40:41]
	v_mov_b32_e32 v37, v193
	v_pk_add_f32 v[36:37], v[64:65], v[36:37]
	ds_bpermute_b32 v15, v119, v36
	ds_bpermute_b32 v11, v119, v37
	v_cndmask_b32_e64 v42, v42, v7, s[40:41]
	v_mov_b32_e32 v45, v39
	v_pk_add_f32 v[42:43], v[42:43], v[44:45]
	v_cvt_pk_bf16_f32 v3, v50, v51
	v_pk_mul_f32 v[38:39], v[158:159], v[42:43] op_sel:[0,1]
	ds_write_b32 v183, v3 offset:128
	v_pk_fma_f32 v[44:45], v[150:151], v[42:43], v[38:39] neg_lo:[0,0,1] neg_hi:[0,0,1]
	v_pk_fma_f32 v[38:39], v[150:151], v[42:43], v[38:39] op_sel_hi:[1,0,1]
	v_cvt_pk_bf16_f32 v3, v52, v53
	v_mov_b32_e32 v45, v39
	s_waitcnt lgkmcnt(1)
	v_cndmask_b32_e64 v39, v11, v37, s[40:41]
	v_cndmask_b32_e64 v38, v15, v36, s[40:41]
	v_pk_add_f32 v[38:39], v[38:39], v[44:45]
	ds_write_b32 v183, v3 offset:400
	v_cndmask_b32_e64 v43, v39, v43, s[40:41]
	v_mov_b32_e32 v4, v43
	v_cvt_pk_bf16_f32 v3, v198, v199
	v_cndmask_b32_e64 v42, v38, v42, s[40:41]
	v_pk_mul_f32 v[44:45], v[160:161], v[4:5] op_sel_hi:[1,0]
	ds_write_b32 v183, v3 offset:672
	v_cvt_pk_bf16_f32 v3, v166, v167
	v_pk_fma_f32 v[48:49], v[78:79], v[42:43], v[44:45] neg_lo:[0,0,1] neg_hi:[0,0,1]
	v_pk_fma_f32 v[44:45], v[78:79], v[42:43], v[44:45] op_sel_hi:[1,0,1]
	ds_write_b32 v185, v3 offset:128
	v_cvt_pk_bf16_f32 v3, v56, v57
	v_mov_b32_e32 v49, v45
	ds_write_b32 v183, v3 offset:2304
	v_cvt_pk_bf16_f32 v3, v212, v213
	v_pk_add_f32 v[44:45], v[190:191], v[48:49]
	v_pk_mul_f32 v[48:49], v[140:141], v[42:43]
	ds_write_b32 v183, v3 offset:2576
	v_cvt_pk_bf16_f32 v3, v54, v55
	v_pk_fma_f32 v[64:65], v[144:145], v[42:43], v[48:49] op_sel:[0,0,1] op_sel_hi:[1,1,0] neg_lo:[0,0,1] neg_hi:[0,0,1]
	v_pk_fma_f32 v[48:49], v[144:145], v[42:43], v[48:49] op_sel:[0,0,1] op_sel_hi:[1,1,0]
	ds_write_b32 v183, v3 offset:2848
	v_cvt_pk_bf16_f32 v3, v214, v215
	v_mov_b32_e32 v65, v49
	v_pk_mul_f32 v[48:49], v[138:139], v[42:43]
	ds_write_b32 v185, v3 offset:2304
	v_cvt_pk_bf16_f32 v3, v58, v59
	v_pk_add_f32 v[46:47], v[46:47], v[64:65]
	v_pk_fma_f32 v[64:65], v[142:143], v[42:43], v[48:49] op_sel:[0,0,1] op_sel_hi:[1,1,0] neg_lo:[0,0,1] neg_hi:[0,0,1]
	v_pk_fma_f32 v[48:49], v[142:143], v[42:43], v[48:49] op_sel:[0,0,1] op_sel_hi:[1,1,0]
	ds_write_b32 v183, v3 offset:4480
	v_cvt_pk_bf16_f32 v3, v60, v61
	v_mov_b32_e32 v65, v49
	ds_write_b32 v183, v3 offset:4752
	v_cvt_pk_bf16_f32 v3, v200, v201
	v_pk_add_f32 v[48:49], v[62:63], v[64:65] op_sel:[1,0] op_sel_hi:[0,1]
	v_pk_mul_f32 v[62:63], v[148:149], v[42:43]
	ds_write_b32 v183, v3 offset:5024
	v_cvt_pk_bf16_f32 v3, v40, v41
	v_pk_fma_f32 v[64:65], v[146:147], v[42:43], v[62:63] op_sel:[0,0,1] op_sel_hi:[1,1,0] neg_lo:[0,0,1] neg_hi:[0,0,1]
	v_pk_fma_f32 v[42:43], v[146:147], v[42:43], v[62:63] op_sel:[0,0,1] op_sel_hi:[1,1,0]
	ds_write_b32 v185, v3 offset:4480
	v_cvt_pk_bf16_f32 v3, v44, v45
	v_mov_b32_e32 v65, v43
	ds_write_b32 v183, v3 offset:6656
	v_cvt_pk_bf16_f32 v3, v46, v47
	v_pk_add_f32 v[42:43], v[36:37], v[64:65]
	ds_write_b32 v183, v3 offset:6928
	v_cvt_pk_bf16_f32 v3, v48, v49
	v_pk_mul_f32 v[40:41], v[156:157], v[184:185] op_sel_hi:[1,0]
	ds_write_b32 v183, v3 offset:7200
	v_cvt_pk_bf16_f32 v3, v42, v43
	v_pk_fma_f32 v[42:43], v[66:67], v[188:189], v[40:41] neg_lo:[0,0,1] neg_hi:[0,0,1]
	v_pk_fma_f32 v[40:41], v[66:67], v[188:189], v[40:41] op_sel_hi:[1,0,1]
	v_mov_b32_e32 v4, v21
	v_mov_b32_e32 v43, v41
	v_pk_add_f32 v[4:5], v[4:5], v[42:43]
	v_pk_mul_f32 v[40:41], v[156:157], v[20:21] op_sel_hi:[1,0]
	ds_bpermute_b32 v7, v119, v5
	ds_bpermute_b32 v21, v119, v4
	v_pk_fma_f32 v[42:43], v[66:67], v[24:25], v[40:41] neg_lo:[0,0,1] neg_hi:[0,0,1]
	v_pk_fma_f32 v[40:41], v[66:67], v[24:25], v[40:41] op_sel_hi:[1,0,1]
	ds_write_b32 v185, v3 offset:6656
	v_mov_b32_e32 v43, v41
	v_pk_mul_f32 v[40:41], v[136:137], v[132:133]
	v_pk_add_f32 v[32:33], v[16:17], v[42:43]
	v_pk_fma_f32 v[42:43], v[154:155], v[132:133], v[40:41] op_sel:[0,0,1] op_sel_hi:[1,1,0] neg_lo:[0,0,1] neg_hi:[0,0,1]
	v_pk_fma_f32 v[40:41], v[154:155], v[132:133], v[40:41] op_sel:[0,0,1] op_sel_hi:[1,1,0]
	s_waitcnt lgkmcnt(2)
; #define LAS __attribute__((address_space(3)))
; __device__ __forceinline__ unsigned pk2(float lo, float hi) { f32x2 v = {lo, hi}; bf16x2_t b = __builtin_convertvector(v, bf16x2_t); return __builtin_bit_cast(unsigned, b); }
; template <bool FIX>
; __device__ __forceinline__ void ssm_block32(const bf16x8& au, const SsmUnit& U, float (&Hr)[2], float (&Hi)[2], float (&H1r)[2], float (&H1i)[2], f32x16 (&Dr)[2], f32x16 (&Di)[2], int h) {
;     ...
;     for (int s = 0; s < 2; ++s) {
;         const float ar = U.pw[s].r[0], ai = U.pw[s].i[0], a4r = U.pw[s].r[3], a4i = U.pw[s].i[3];
; #pragma unroll
;         for (int j = 0; j < 4; ++j)
; #pragma unroll
;             for (int e = 1; e < 4; ++e) { const int i = 4 * j + e;
;                 const float nr = ar * Dr[s][i - 1] - ai * Di[s][i - 1] + Dr[s][i], ni = ar * Di[s][i - 1] + ai * Dr[s][i - 1] + Di[s][i]; Dr[s][i] = nr; Di[s][i] = ni; }
;         float hr = Hr[s], hi = Hi[s];
; #pragma unroll
;         for (int j = 0; j < 4; ++j) {
;             const float ownr = Dr[s][4 * j + 3], owni = Di[s][4 * j + 3], othr = __shfl_xor(ownr, 32), othi = __shfl_xor(owni, 32);
;             const float evr = h ? othr : ownr, evi = h ? othi : owni, odr = h ? ownr : othr, odi = h ? owni : othi;
;             const float inr0 = hr, ini0 = hi;
;             float t = a4r * hr - a4i * hi + evr; hi = a4r * hi + a4i * hr + evi; hr = t;
;             if (j == 0) { H1r[s] = hr; H1i[s] = hi; }
;             const float inr1 = hr, ini1 = hi;
;             t = a4r * hr - a4i * hi + odr; hi = a4r * hi + a4i * hr + odi; hr = t;
;             if (FIX) { const float inr = h ? inr1 : inr0, ini = h ? ini1 : ini0;
; #pragma unroll
;                 for (int e = 0; e < 4; ++e) { const int i = 4 * j + e; Dr[s][i] += U.pw[s].r[e] * inr - U.pw[s].i[e] * ini; Di[s][i] += U.pw[s].r[e] * ini + U.pw[s].i[e] * inr; } }
;         }
;         Hr[s] = hr; Hi[s] = hi;
; __device__ __forceinline__ void s3_ssm_pass2(Frame& F, int l) {
;     ...
; #pragma unroll
;             for (int i = 0; i < 16; ++i) { const int tl = (i & 3) + 8 * (i >> 2) + 4 * h;
;                 *(LAS unsigned*)(himg + tl * 272 + 4 * n32) = pk2(Dr[0][i], Di[0][i]); *(LAS unsigned*)(himg + tl * 272 + 4 * (32 + n32)) = pk2(Dr[1][i], Di[1][i]); }
	v_cndmask_b32_e64 v17, v7, v5, s[40:41]
	s_waitcnt lgkmcnt(1)
	v_cndmask_b32_e64 v16, v21, v4, s[40:41]
	v_mov_b32_e32 v43, v41
	v_pk_add_f32 v[16:17], v[42:43], v[16:17]
	v_pk_mul_f32 v[44:45], v[156:157], v[180:181] op_sel_hi:[1,0]
	v_cndmask_b32_e64 v12, v17, v133, s[40:41]
	v_cndmask_b32_e64 v8, v16, v132, s[40:41]
	v_pk_mul_f32 v[40:41], v[66:67], v[12:13] op_sel_hi:[1,0]
	v_pk_fma_f32 v[46:47], v[66:67], v[182:183], v[44:45] neg_lo:[0,0,1] neg_hi:[0,0,1]
	v_pk_fma_f32 v[42:43], v[66:67], v[8:9], v[40:41] op_sel:[0,0,1] op_sel_hi:[1,1,0] neg_lo:[0,0,1] neg_hi:[0,0,1]
	v_pk_fma_f32 v[40:41], v[66:67], v[8:9], v[40:41] op_sel:[0,0,1] op_sel_hi:[1,0,0]
	v_pk_fma_f32 v[44:45], v[66:67], v[182:183], v[44:45] op_sel_hi:[1,0,1]
	v_mov_b32_e32 v43, v41
	v_pk_add_f32 v[2:3], v[18:19], v[42:43]
	v_mul_f32_e32 v18, v81, v12
	v_fma_f32 v18, v68, v8, -v18
	v_add_f32_e32 v54, v186, v18
	v_mul_f32_e32 v18, v81, v8
	v_fmac_f32_e32 v18, v68, v12
	v_add_f32_e32 v55, v187, v18
	v_mul_f32_e32 v18, v131, v12
	v_fma_f32 v18, v208, v8, -v18
	v_add_f32_e32 v56, v188, v18
	v_mul_f32_e32 v18, v131, v8
	v_fmac_f32_e32 v18, v208, v12
	v_add_f32_e32 v57, v184, v18
	v_pk_mul_f32 v[18:19], v[134:135], v[12:13] op_sel_hi:[1,0]
	v_mov_b32_e32 v47, v45
	v_pk_fma_f32 v[40:41], v[134:135], v[8:9], v[18:19] op_sel:[0,0,1] op_sel_hi:[1,1,0] neg_lo:[0,0,1] neg_hi:[0,0,1]
	v_pk_fma_f32 v[18:19], v[134:135], v[8:9], v[18:19] op_sel:[0,0,1] op_sel_hi:[1,0,0]
	v_pk_mul_f32 v[44:45], v[156:157], v[28:29] op_sel_hi:[1,0]
	v_mov_b32_e32 v41, v19
	v_pk_add_f32 v[18:19], v[4:5], v[40:41]
	v_pk_mul_f32 v[40:41], v[136:137], v[16:17] op_sel:[0,1] op_sel_hi:[1,0]
	v_cndmask_b32_e64 v5, v5, v7, s[40:41]
	v_pk_fma_f32 v[42:43], v[154:155], v[16:17], v[40:41] neg_lo:[0,0,1] neg_hi:[0,0,1]
	v_pk_fma_f32 v[40:41], v[154:155], v[16:17], v[40:41]
	v_cndmask_b32_e64 v4, v4, v21, s[40:41]
	v_mov_b32_e32 v43, v41
	v_pk_add_f32 v[4:5], v[4:5], v[42:43]
	v_mov_b32_e32 v12, v29
	v_mul_f32_e32 v8, v135, v5
	v_pk_fma_f32 v[40:41], v[134:135], v[4:5], v[8:9] op_sel_hi:[1,1,0] neg_lo:[0,0,1] neg_hi:[0,0,1]
	v_mul_f32_e32 v8, v134, v5
	v_pk_fma_f32 v[42:43], v[134:135], v[4:5], v[8:9] op_sel:[0,1,0] op_sel_hi:[1,0,0]
	v_mov_b32_e32 v8, v25
	v_pk_add_f32 v[8:9], v[8:9], v[46:47]
	ds_bpermute_b32 v7, v119, v9
	ds_bpermute_b32 v21, v119, v8
	v_pk_fma_f32 v[46:47], v[66:67], v[176:177], v[44:45] neg_lo:[0,0,1] neg_hi:[0,0,1]
	v_pk_fma_f32 v[44:45], v[66:67], v[176:177], v[44:45] op_sel_hi:[1,0,1]
	v_mov_b32_e32 v41, v43
	v_mov_b32_e32 v47, v45
	v_pk_add_f32 v[12:13], v[12:13], v[46:47]
	s_waitcnt lgkmcnt(1)
	v_cndmask_b32_e64 v45, v7, v9, s[40:41]
	s_waitcnt lgkmcnt(0)
	v_cndmask_b32_e64 v44, v21, v8, s[40:41]
	ds_bpermute_b32 v23, v119, v13
	v_pk_add_f32 v[40:41], v[44:45], v[40:41]
	ds_bpermute_b32 v25, v119, v12
	v_pk_mul_f32 v[42:43], v[136:137], v[40:41]
	v_cndmask_b32_e64 v4, v40, v4, s[40:41]
	v_pk_fma_f32 v[44:45], v[154:155], v[40:41], v[42:43] op_sel:[0,0,1] op_sel_hi:[1,1,0] neg_lo:[0,0,1] neg_hi:[0,0,1]
	v_pk_fma_f32 v[42:43], v[154:155], v[40:41], v[42:43] op_sel:[0,0,1] op_sel_hi:[1,1,0]
	v_cndmask_b32_e64 v40, v41, v5, s[40:41]
	v_mov_b32_e32 v45, v43
	v_pk_mul_f32 v[42:43], v[66:67], v[40:41] op_sel_hi:[1,0]
	s_waitcnt lgkmcnt(1)
	v_cndmask_b32_e64 v49, v23, v13, s[40:41]
	v_pk_fma_f32 v[52:53], v[66:67], v[4:5], v[42:43] op_sel:[0,0,1] op_sel_hi:[1,1,0] neg_lo:[0,0,1] neg_hi:[0,0,1]
	v_pk_fma_f32 v[42:43], v[66:67], v[4:5], v[42:43] op_sel:[0,0,1] op_sel_hi:[1,0,0]
	v_mul_f32_e32 v5, v81, v40
	v_cndmask_b32_e64 v51, v13, v23, s[40:41]
	v_mov_b32_e32 v53, v43
	v_mov_b32_e32 v23, v6
	v_fma_f32 v5, v68, v4, -v5
	v_pk_add_f32 v[22:23], v[22:23], v[52:53]
	v_add_f32_e32 v52, v178, v5
	v_mul_f32_e32 v5, v81, v4
	v_fmac_f32_e32 v5, v68, v40
	v_add_f32_e32 v53, v179, v5
	v_mul_f32_e32 v5, v131, v40
	v_fma_f32 v5, v208, v4, -v5
	v_add_f32_e32 v58, v182, v5
	v_mul_f32_e32 v5, v131, v4
	v_cndmask_b32_e64 v47, v9, v7, s[40:41]
	v_fmac_f32_e32 v5, v208, v40
	v_pk_mul_f32 v[6:7], v[134:135], v[40:41] op_sel_hi:[1,0]
	v_cndmask_b32_e64 v46, v8, v21, s[40:41]
	v_add_f32_e32 v59, v180, v5
	v_pk_fma_f32 v[40:41], v[134:135], v[4:5], v[6:7] op_sel:[0,0,1] op_sel_hi:[1,1,0] neg_lo:[0,0,1] neg_hi:[0,0,1]
	v_pk_fma_f32 v[4:5], v[134:135], v[4:5], v[6:7] op_sel:[0,0,1] op_sel_hi:[1,0,0]
	v_pk_add_f32 v[6:7], v[46:47], v[44:45]
	v_mov_b32_e32 v41, v5
	v_pk_add_f32 v[4:5], v[8:9], v[40:41]
	v_pk_mul_f32 v[8:9], v[136:137], v[6:7]
	s_waitcnt lgkmcnt(0)
	v_cndmask_b32_e64 v48, v25, v12, s[40:41]
	v_pk_fma_f32 v[40:41], v[154:155], v[6:7], v[8:9] op_sel:[0,0,1] op_sel_hi:[1,1,0] neg_lo:[0,0,1] neg_hi:[0,0,1]
	v_pk_fma_f32 v[8:9], v[154:155], v[6:7], v[8:9] op_sel:[0,0,1] op_sel_hi:[1,1,0]
	v_cndmask_b32_e64 v50, v12, v25, s[40:41]
	v_mov_b32_e32 v41, v9
	v_pk_add_f32 v[8:9], v[48:49], v[40:41]
	v_cvt_pk_bf16_f32 v2, v2, v3
	v_pk_mul_f32 v[40:41], v[136:137], v[8:9]
	v_cndmask_b32_e64 v6, v8, v6, s[40:41]
	v_pk_fma_f32 v[42:43], v[154:155], v[8:9], v[40:41] op_sel:[0,0,1] op_sel_hi:[1,1,0] neg_lo:[0,0,1] neg_hi:[0,0,1]
	v_pk_fma_f32 v[40:41], v[154:155], v[8:9], v[40:41] op_sel:[0,0,1] op_sel_hi:[1,1,0]
	v_cndmask_b32_e64 v8, v9, v7, s[40:41]
	v_mov_b32_e32 v43, v41
	v_pk_mul_f32 v[40:41], v[66:67], v[8:9] op_sel_hi:[1,0]
	ds_write_b32 v183, v2
	v_pk_fma_f32 v[44:45], v[66:67], v[6:7], v[40:41] op_sel:[0,0,1] op_sel_hi:[1,1,0] neg_lo:[0,0,1] neg_hi:[0,0,1]
	v_pk_fma_f32 v[40:41], v[66:67], v[6:7], v[40:41] op_sel:[0,0,1] op_sel_hi:[1,0,0]
	v_mul_f32_e32 v7, v81, v8
	v_mov_b32_e32 v45, v41
	v_fma_f32 v7, v68, v6, -v7
	v_pk_add_f32 v[26:27], v[26:27], v[44:45]
	v_add_f32_e32 v44, v174, v7
	v_mul_f32_e32 v7, v81, v6
	v_fmac_f32_e32 v7, v68, v8
	v_add_f32_e32 v45, v175, v7
	v_mul_f32_e32 v7, v131, v8
	v_fma_f32 v7, v208, v6, -v7
	v_add_f32_e32 v46, v176, v7
	v_mul_f32_e32 v7, v131, v6
	v_fmac_f32_e32 v7, v208, v8
	v_pk_mul_f32 v[8:9], v[134:135], v[8:9] op_sel_hi:[1,0]
	v_add_f32_e32 v47, v28, v7
	v_pk_fma_f32 v[28:29], v[134:135], v[6:7], v[8:9] op_sel:[0,0,1] op_sel_hi:[1,1,0] neg_lo:[0,0,1] neg_hi:[0,0,1]
	v_pk_fma_f32 v[6:7], v[134:135], v[6:7], v[8:9] op_sel:[0,0,1] op_sel_hi:[1,0,0]
	ds_bpermute_b32 v9, v119, v33
	ds_bpermute_b32 v8, v119, v32
	v_mov_b32_e32 v29, v7
	v_pk_add_f32 v[12:13], v[12:13], v[28:29]
	v_pk_add_f32 v[28:29], v[50:51], v[42:43]
	v_cvt_pk_bf16_f32 v2, v54, v55
	v_pk_mul_f32 v[40:41], v[136:137], v[28:29]
	s_waitcnt lgkmcnt(1)
; #define LAS __attribute__((address_space(3)))
; __device__ __forceinline__ unsigned pk2(float lo, float hi) { f32x2 v = {lo, hi}; bf16x2_t b = __builtin_convertvector(v, bf16x2_t); return __builtin_bit_cast(unsigned, b); }
; __device__ __forceinline__ float gelu_tanh(float y) { const float a = 1.5957691216f * (y + 0.044715f * y * y * y); return y * sigmoidf_(a); }
; #define LDS_WAIT() asm volatile("s_waitcnt lgkmcnt(0)" ::: "memory")
; __device__ __forceinline__ f32x4 unpack4(const u32x2& x) { return (f32x4){bf2f(x.x & 0xffffu), __uint_as_float(x.x & 0xffff0000u), bf2f(x.y & 0xffffu), __uint_as_float(x.y & 0xffff0000u)}; }
; __device__ __forceinline__ void s3_ssm_pass2(Frame& F, int l) {
;     ...
; #pragma unroll
;             for (int i = 0; i < 16; ++i) { const int tl = (i & 3) + 8 * (i >> 2) + 4 * h;
;                 *(LAS unsigned*)(himg + tl * 272 + 4 * n32) = pk2(Dr[0][i], Di[0][i]); *(LAS unsigned*)(himg + tl * 272 + 4 * (32 + n32)) = pk2(Dr[1][i], Di[1][i]); }
;             LDS_WAIT(); asm volatile("" ::: "memory");
; #pragma unroll
;             for (int tt = 0; tt < 2; ++tt) {
;                 f32x4 y = {0.f, 0.f, 0.f, 0.f};
; #pragma unroll
;                 for (int ks = 0; ks < 4; ++ks) { const bf16x8 hf = *(const LAS bf16x8*)(himg + (16 * tt + tk) * 272 + (32 * ks + 8 * cq) * 2); y = __builtin_amdgcn_mfma_f32_16x16x32_bf16(cmf[ks], hf, y, 0, 0, 0); }
;                 const int t = 32 * blk + 16 * tt + tk;
;                 if (16 * tt + tk < ntok) { const f32x4 uu = unpack4(uw[tt]);
;                     u32x2 o; o.x = pk2(gelu_tanh(y.x + ds.x * uu.x), gelu_tanh(y.y + ds.y * uu.y)); o.y = pk2(gelu_tanh(y.z + ds.z * uu.z), gelu_tanh(y.w + ds.w * uu.w));
;                     *(u32x2*)(Z + (size_t)(m0 + t) * 1024 + g * 16 + 4 * cq) = o; }
	v_cndmask_b32_e64 v7, v9, v33, s[40:41]
	v_pk_fma_f32 v[42:43], v[154:155], v[28:29], v[40:41] op_sel:[0,0,1] op_sel_hi:[1,1,0] neg_lo:[0,0,1] neg_hi:[0,0,1]
	v_pk_fma_f32 v[40:41], v[154:155], v[28:29], v[40:41] op_sel:[0,0,1] op_sel_hi:[1,1,0]
	s_waitcnt lgkmcnt(0)
	v_cndmask_b32_e64 v6, v8, v32, s[40:41]
	v_mov_b32_e32 v43, v41
	ds_write_b32 v183, v2 offset:272
	v_cvt_pk_bf16_f32 v2, v56, v57
	v_pk_add_f32 v[6:7], v[6:7], v[42:43]
	ds_write_b32 v183, v2 offset:544
	v_cvt_pk_bf16_f32 v2, v18, v19
	v_cndmask_b32_e64 v10, v6, v28, s[40:41]
	ds_write_b32 v185, v2
	v_cvt_pk_bf16_f32 v2, v22, v23
	v_cndmask_b32_e64 v28, v7, v29, s[40:41]
	v_mul_f32_e32 v21, v81, v10
	ds_write_b32 v183, v2 offset:2176
	v_cvt_pk_bf16_f32 v2, v52, v53
	v_fmac_f32_e32 v21, v68, v28
	ds_write_b32 v183, v2 offset:2448
	v_cvt_pk_bf16_f32 v2, v58, v59
	v_pk_mul_f32 v[40:41], v[66:67], v[28:29] op_sel_hi:[1,0]
	v_add_f32_e32 v29, v173, v21
	v_mul_f32_e32 v21, v131, v28
	ds_write_b32 v183, v2 offset:2720
	v_cvt_pk_bf16_f32 v2, v4, v5
	v_pk_fma_f32 v[42:43], v[66:67], v[10:11], v[40:41] op_sel:[0,0,1] op_sel_hi:[1,1,0] neg_lo:[0,0,1] neg_hi:[0,0,1]
	v_pk_fma_f32 v[40:41], v[66:67], v[10:11], v[40:41] op_sel:[0,0,1] op_sel_hi:[1,0,0]
	v_fma_f32 v21, v208, v10, -v21
	ds_write_b32 v185, v2 offset:2176
	v_cvt_pk_bf16_f32 v2, v26, v27
	v_add_f32_e32 v40, v24, v21
	v_mul_f32_e32 v21, v131, v10
	ds_write_b32 v183, v2 offset:4352
	v_cvt_pk_bf16_f32 v2, v44, v45
	v_mov_b32_e32 v43, v41
	v_mul_f32_e32 v14, v81, v28
	v_fmac_f32_e32 v21, v208, v28
	ds_write_b32 v183, v2 offset:4624
	v_cvt_pk_bf16_f32 v2, v46, v47
	v_pk_add_f32 v[30:31], v[30:31], v[42:43]
	v_fma_f32 v14, v68, v10, -v14
	v_add_f32_e32 v41, v20, v21
	v_pk_mul_f32 v[20:21], v[134:135], v[28:29] op_sel_hi:[1,0]
	ds_write_b32 v183, v2 offset:4896
	v_cvt_pk_bf16_f32 v2, v12, v13
	v_add_f32_e32 v14, v172, v14
	v_pk_fma_f32 v[24:25], v[134:135], v[10:11], v[20:21] op_sel:[0,0,1] op_sel_hi:[1,1,0] neg_lo:[0,0,1] neg_hi:[0,0,1]
	v_pk_fma_f32 v[20:21], v[134:135], v[10:11], v[20:21] op_sel:[0,0,1] op_sel_hi:[1,0,0]
	ds_write_b32 v185, v2 offset:4352
	v_cvt_pk_bf16_f32 v2, v30, v31
	v_mov_b32_e32 v25, v21
	ds_write_b32 v183, v2 offset:6528
	v_cvt_pk_bf16_f32 v2, v14, v29
	v_pk_add_f32 v[20:21], v[32:33], v[24:25]
	ds_write_b32 v183, v2 offset:6800
	v_cvt_pk_bf16_f32 v2, v40, v41
	ds_write_b32 v183, v2 offset:7072
	v_cvt_pk_bf16_f32 v2, v20, v21
	ds_write_b32 v185, v2 offset:6528
	s_waitcnt lgkmcnt(0)
	ds_read_b128 v[2:5], v189
	ds_read_b128 v[18:21], v189 offset:64
	s_waitcnt lgkmcnt(1)
	v_mfma_f32_16x16x32_bf16 v[2:5], v[90:93], v[2:5], 0
	s_waitcnt lgkmcnt(0)
	v_mfma_f32_16x16x32_bf16 v[2:5], v[94:97], v[18:21], v[2:5]
	ds_read_b128 v[18:21], v189 offset:128
	ds_read_b128 v[22:25], v189 offset:192
	s_waitcnt lgkmcnt(1)
	v_mfma_f32_16x16x32_bf16 v[2:5], v[100:103], v[18:21], v[2:5]
	s_waitcnt lgkmcnt(0)
	v_mfma_f32_16x16x32_bf16 v[2:5], v[104:107], v[22:25], v[2:5]
	s_waitcnt vmcnt(0)
	s_and_saveexec_b64 s[22:23], s[46:47]
	s_cbranch_execz .LBB0_721
	v_lshlrev_b32_e32 v12, 16, v170
	v_and_b32_e32 v13, 0xffff0000, v170
	s_nop 3
	v_pk_fma_f32 v[2:3], v[108:109], v[12:13], v[2:3]
	v_ashrrev_i32_e32 v169, 31, v168
	v_mul_f32_e32 v10, 0x3d372713, v2
	v_mul_f32_e32 v10, v2, v10
	v_fma_f32 v10, v2, v10, v2
	v_mul_f32_e32 v10, 0x3fcc422a, v10
	v_mul_f32_e32 v10, 0xbfb8aa3b, v10
	v_exp_f32_e32 v10, v10
	s_nop 0
	v_add_f32_e32 v10, 1.0, v10
	v_rcp_f32_e32 v12, v10
	v_mul_f32_e32 v10, 0x3d372713, v3
	v_mul_f32_e32 v10, v3, v10
	v_fma_f32 v10, v3, v10, v3
	v_mul_f32_e32 v10, 0x3fcc422a, v10
	v_mul_f32_e32 v10, 0xbfb8aa3b, v10
	v_exp_f32_e32 v10, v10
	s_nop 0
	v_add_f32_e32 v10, 1.0, v10
	v_rcp_f32_e32 v13, v10
	s_nop 0
	v_pk_mul_f32 v[2:3], v[2:3], v[12:13]
	v_lshlrev_b32_e32 v12, 16, v171
	v_and_b32_e32 v13, 0xffff0000, v171
	v_pk_fma_f32 v[4:5], v[110:111], v[12:13], v[4:5]
	v_cvt_pk_bf16_f32 v2, v2, v3
	v_mul_f32_e32 v3, 0x3d372713, v4
	v_mul_f32_e32 v3, v4, v3
	v_fma_f32 v3, v4, v3, v4
	v_mul_f32_e32 v3, 0x3fcc422a, v3
	v_mul_f32_e32 v3, 0xbfb8aa3b, v3
	v_exp_f32_e32 v3, v3
	s_nop 0
	v_add_f32_e32 v3, 1.0, v3
	v_rcp_f32_e32 v12, v3
	v_mul_f32_e32 v3, 0x3d372713, v5
	v_mul_f32_e32 v3, v5, v3
	v_fma_f32 v3, v5, v3, v5
	v_mul_f32_e32 v3, 0x3fcc422a, v3
	v_mul_f32_e32 v3, 0xbfb8aa3b, v3
	v_exp_f32_e32 v3, v3
	s_nop 0
	v_add_f32_e32 v3, 1.0, v3
	v_rcp_f32_e32 v13, v3
	s_nop 0
	v_pk_mul_f32 v[4:5], v[4:5], v[12:13]
	s_nop 0
	v_cvt_pk_bf16_f32 v3, v4, v5
	v_lshlrev_b64 v[4:5], 11, v[168:169]
	v_lshl_add_u64 v[4:5], v[152:153], 0, v[4:5]
	global_store_dwordx2 v[4:5], v[2:3], off

; __device__ __forceinline__ void s3_ssm_pass2(Frame& F, int l) {
;     ...
; #pragma unroll 1
;         for (int blk = 0; blk < nblk; ++blk) {
;             const bf16x8 an = ssm_load_au(P, m0 + 32 * ((blk + 1) & 3), ntok, g, lane);
;             u32x2 uw[2];
; #pragma unroll
;             for (int tt = 0; tt < 2; ++tt) uw[tt] = (16 * tt + tk < ntok) ? *(const u32x2*)(P + (size_t)(m0 + 32 * blk + 16 * tt + tk) * NPROJ + C_SU + g * 16 + 4 * cq) : (u32x2){0u, 0u};
;             f32x16 Dr[2], Di[2];
;             ssm_block32<true>(au, U, Hr, Hi, H1r, H1i, Dr, Di, h);
;             au = an;
.LBB0_723:
	s_or_b64 exec, exec, s[22:23]
	s_nop 4
	v_pk_mul_f32 v[2:3], v[150:151], v[38:39]
	v_cndmask_b32_e64 v4, v36, v15, s[40:41]
	v_sub_f32_e32 v2, v2, v3
	v_add_f32_e32 v166, v4, v2
	v_pk_mul_f32 v[2:3], v[136:137], v[6:7]
	v_cndmask_b32_e64 v5, v33, v9, s[40:41]
	v_cndmask_b32_e64 v4, v32, v8, s[40:41]
	v_pk_fma_f32 v[8:9], v[154:155], v[6:7], v[2:3] op_sel:[0,0,1] op_sel_hi:[1,1,0] neg_lo:[0,0,1] neg_hi:[0,0,1]
	v_pk_fma_f32 v[2:3], v[154:155], v[6:7], v[2:3] op_sel:[0,0,1] op_sel_hi:[1,1,0]
	s_waitcnt lgkmcnt(0)
	s_add_i32 s24, s24, 32
	v_mul_f32_e32 v2, v80, v38
	v_mov_b32_e32 v9, v3
	v_fmac_f32_e32 v2, v150, v39
	v_cndmask_b32_e64 v3, v37, v11, s[40:41]
	v_pk_add_f32 v[132:133], v[4:5], v[8:9]
	v_add_f32_e32 v167, v3, v2
	s_cmp_eq_u32 s25, s24
	s_cbranch_scc1 .LBB0_725
	s_waitcnt vmcnt(4)
	v_mov_b32_e32 v50, v112
	v_mov_b32_e32 v51, v113
	v_mov_b32_e32 v52, v114
	v_mov_b32_e32 v53, v115
	s_branch .LBB0_713
